# gated-branch GEMM epilogue rewritten by hand: gate loads batched 8 at a time with counted waits instead of one round trip per 8 columns
# baseline (speedup 1.0000x reference)
;     __device__ __forceinline__ bool apply(f32x4 (&acc)[2][2][4][2], const pg8::Unit& u, int wr, int wc, int fr, int fq) const {
;         if (kind != K_BR3) { (*this)(acc, u, wr, wc, fr, fq); return false; }
;         const int row0 = u.pm * 256 + wr * 64 + fr, colb = u.pn * 256 + wc * 32 + 8 * fq, br = u.br;
.LBB0_462:
	s_cmp_eq_u32 s28, 8
	s_cbranch_scc1 .Lbr_epi
	s_cmp_eq_u32 s28, 5
	s_cbranch_scc1 .Lwo_epi
	s_cmp_eq_u32 s28, 7
	s_cbranch_scc0 .Lfx_no
	v_readlane_b32 s98, v255, 12
	s_cmpk_gt_u32 s98, 24
	s_cbranch_scc1 .Lfn_epi

;     __device__ __forceinline__ bool apply(f32x4 (&acc)[2][2][4][2], const pg8::Unit& u, int wr, int wc, int fr, int fq) const {
;     ...
;         const int row0 = u.pm * 256 + wr * 64 + fr, colb = u.pn * 256 + wc * 32 + 8 * fq, br = u.br;
;         const bf16_t* G = (const bf16_t*)(ws + WS_GATE); bf16_t* Mb = (bf16_t*)(ws + WS_HB);
; #pragma unroll
;         for (int ai = 0; ai < 2; ++ai)
; #pragma unroll
;             for (int m = 0; m < 4; ++m)
; #pragma unroll
;                 for (int bj = 0; bj < 2; ++bj) { const int row = row0 + ai * 128 + m * 16, col0 = colb + bj * 128;
;                     float gc[8], gn[8]; load8(G + (size_t)row * GT_COLS + br * 1024 + col0, gc);
;                     if (br < 2) load8(G + (size_t)row * GT_COLS + (br + 1) * 1024 + col0, gn);
;                     else {
; #pragma unroll
;                         for (int j = 0; j < 8; ++j) gn[j] = 1.f; }
;                     float v[8]; const f32x4 v0 = acc[ai][bj][m][0], v1 = acc[ai][bj][m][1];
;                     v[0] = v0.x; v[1] = v0.y; v[2] = v0.z; v[3] = v0.w; v[4] = v1.x; v[5] = v1.y; v[6] = v1.z; v[7] = v1.w;
; #pragma unroll
;                     for (int j = 0; j < 8; ++j) v[j] *= fmaxf(gc[j], 1e-4f);
;                     if (br == 2) store8(Mb + (size_t)row * 1024 + col0, v);
;                     else {
; #pragma unroll
;                         for (int j = 0; j < 8; ++j) v[j] *= __builtin_amdgcn_rcpf(fmaxf(gn[j], 1e-4f));
;                         acc[ai][bj][m][0] = (f32x4){v[0], v[1], v[2], v[3]}; acc[ai][bj][m][1] = (f32x4){v[4], v[5], v[6], v[7]}; }
;                 }
;         return br < 2;
.Lbr_epi:
	v_lshl_add_u32 v202, s43, 8, v186
	s_lshl_b32 s98, s42, 8
	v_or_b32_e32 v203, s98, v188
	v_mul_u32_u24_e32 v242, 0x1800, v202
	v_lshl_add_u32 v242, v203, 1, v242
	s_lshl_b32 s98, s15, 11
	v_add_u32_e32 v242, s98, v242
	v_mov_b32_e32 v182, v242
	v_add_u32_e32 v183, 0x18000, v242
	v_add_u32_e32 v184, 0x30000, v242
	v_add_u32_e32 v185, 0x48000, v242
	v_add_u32_e32 v190, 0xc0000, v242
	v_add_u32_e32 v191, 0xd8000, v242
	v_add_u32_e32 v200, 0xf0000, v242
	v_add_u32_e32 v201, 0x108000, v242
	s_cmp_eq_u32 s15, 2
	s_cbranch_scc1 .Lbr_last
	global_load_dwordx4 v[210:213], v182, s[4:5]
	global_load_dwordx4 v[214:217], v182, s[4:5] offset:2048
	global_load_dwordx4 v[218:221], v182, s[4:5] offset:256
	global_load_dwordx4 v[222:225], v182, s[4:5] offset:2304
	global_load_dwordx4 v[226:229], v183, s[4:5]
	global_load_dwordx4 v[230:233], v183, s[4:5] offset:2048
	global_load_dwordx4 v[234:237], v183, s[4:5] offset:256
	global_load_dwordx4 v[238:241], v183, s[4:5] offset:2304
	global_load_dwordx4 v[132:135], v184, s[4:5]
	global_load_dwordx4 v[136:139], v184, s[4:5] offset:2048
	global_load_dwordx4 v[140:143], v184, s[4:5] offset:256
	global_load_dwordx4 v[144:147], v184, s[4:5] offset:2304
	global_load_dwordx4 v[148:151], v185, s[4:5]
	global_load_dwordx4 v[152:155], v185, s[4:5] offset:2048
	global_load_dwordx4 v[156:159], v185, s[4:5] offset:256
	global_load_dwordx4 v[160:163], v185, s[4:5] offset:2304
	s_waitcnt vmcnt(8)
	v_lshlrev_b32_e32 v244, 16, v210
	v_and_b32_e32 v245, 0xffff0000, v210
	v_lshlrev_b32_e32 v246, 16, v211
	v_and_b32_e32 v247, 0xffff0000, v211
	v_lshlrev_b32_e32 v248, 16, v212
	v_and_b32_e32 v249, 0xffff0000, v212
	v_lshlrev_b32_e32 v250, 16, v213
	v_and_b32_e32 v251, 0xffff0000, v213
	v_max_f32_e32 v244, 0x38d1b717, v244
	v_max_f32_e32 v245, 0x38d1b717, v245
	v_max_f32_e32 v246, 0x38d1b717, v246
	v_max_f32_e32 v247, 0x38d1b717, v247
	v_max_f32_e32 v248, 0x38d1b717, v248
	v_max_f32_e32 v249, 0x38d1b717, v249
	v_max_f32_e32 v250, 0x38d1b717, v250
	v_max_f32_e32 v251, 0x38d1b717, v251
	v_pk_mul_f32 v[128:129], v[128:129], v[244:245]
	v_pk_mul_f32 v[130:131], v[130:131], v[246:247]
	v_pk_mul_f32 v[124:125], v[124:125], v[248:249]
	v_pk_mul_f32 v[126:127], v[126:127], v[250:251]
	v_lshlrev_b32_e32 v244, 16, v214
	v_and_b32_e32 v245, 0xffff0000, v214
	v_lshlrev_b32_e32 v246, 16, v215
	v_and_b32_e32 v247, 0xffff0000, v215
	v_lshlrev_b32_e32 v248, 16, v216
	v_and_b32_e32 v249, 0xffff0000, v216
	v_lshlrev_b32_e32 v250, 16, v217
	v_and_b32_e32 v251, 0xffff0000, v217
	v_max_f32_e32 v244, 0x38d1b717, v244
	v_max_f32_e32 v245, 0x38d1b717, v245
	v_max_f32_e32 v246, 0x38d1b717, v246
	v_max_f32_e32 v247, 0x38d1b717, v247
	v_max_f32_e32 v248, 0x38d1b717, v248
	v_max_f32_e32 v249, 0x38d1b717, v249
	v_max_f32_e32 v250, 0x38d1b717, v250
	v_max_f32_e32 v251, 0x38d1b717, v251
	v_rcp_f32_e32 v244, v244
	v_rcp_f32_e32 v245, v245
	v_rcp_f32_e32 v246, v246
	v_rcp_f32_e32 v247, v247
	v_rcp_f32_e32 v248, v248
	v_rcp_f32_e32 v249, v249
	v_rcp_f32_e32 v250, v250
	v_rcp_f32_e32 v251, v251
	s_nop 0
	v_pk_mul_f32 v[128:129], v[128:129], v[244:245]
	v_pk_mul_f32 v[130:131], v[130:131], v[246:247]
	v_pk_mul_f32 v[124:125], v[124:125], v[248:249]
	v_pk_mul_f32 v[126:127], v[126:127], v[250:251]
	v_lshlrev_b32_e32 v244, 16, v218
	v_and_b32_e32 v245, 0xffff0000, v218
	v_lshlrev_b32_e32 v246, 16, v219
	v_and_b32_e32 v247, 0xffff0000, v219
	v_lshlrev_b32_e32 v248, 16, v220
	v_and_b32_e32 v249, 0xffff0000, v220
	v_lshlrev_b32_e32 v250, 16, v221
	v_and_b32_e32 v251, 0xffff0000, v221
	v_max_f32_e32 v244, 0x38d1b717, v244
	v_max_f32_e32 v245, 0x38d1b717, v245
	v_max_f32_e32 v246, 0x38d1b717, v246
	v_max_f32_e32 v247, 0x38d1b717, v247
	v_max_f32_e32 v248, 0x38d1b717, v248
	v_max_f32_e32 v249, 0x38d1b717, v249
	v_max_f32_e32 v250, 0x38d1b717, v250
	v_max_f32_e32 v251, 0x38d1b717, v251
	v_pk_mul_f32 v[120:121], v[120:121], v[244:245]
	v_pk_mul_f32 v[122:123], v[122:123], v[246:247]
	v_pk_mul_f32 v[116:117], v[116:117], v[248:249]
	v_pk_mul_f32 v[118:119], v[118:119], v[250:251]
	v_lshlrev_b32_e32 v244, 16, v222
	v_and_b32_e32 v245, 0xffff0000, v222
	v_lshlrev_b32_e32 v246, 16, v223
	v_and_b32_e32 v247, 0xffff0000, v223
	v_lshlrev_b32_e32 v248, 16, v224
	v_and_b32_e32 v249, 0xffff0000, v224
	v_lshlrev_b32_e32 v250, 16, v225
	v_and_b32_e32 v251, 0xffff0000, v225
	v_max_f32_e32 v244, 0x38d1b717, v244
	v_max_f32_e32 v245, 0x38d1b717, v245
	v_max_f32_e32 v246, 0x38d1b717, v246
	v_max_f32_e32 v247, 0x38d1b717, v247
	v_max_f32_e32 v248, 0x38d1b717, v248
	v_max_f32_e32 v249, 0x38d1b717, v249
	v_max_f32_e32 v250, 0x38d1b717, v250
	v_max_f32_e32 v251, 0x38d1b717, v251
	v_rcp_f32_e32 v244, v244
	v_rcp_f32_e32 v245, v245
	v_rcp_f32_e32 v246, v246
	v_rcp_f32_e32 v247, v247
	v_rcp_f32_e32 v248, v248
	v_rcp_f32_e32 v249, v249
	v_rcp_f32_e32 v250, v250
	v_rcp_f32_e32 v251, v251
	s_nop 0
	v_pk_mul_f32 v[120:121], v[120:121], v[244:245]
	v_pk_mul_f32 v[122:123], v[122:123], v[246:247]
	v_pk_mul_f32 v[116:117], v[116:117], v[248:249]
	v_pk_mul_f32 v[118:119], v[118:119], v[250:251]
	v_lshlrev_b32_e32 v244, 16, v226
	v_and_b32_e32 v245, 0xffff0000, v226
	v_lshlrev_b32_e32 v246, 16, v227
	v_and_b32_e32 v247, 0xffff0000, v227
	v_lshlrev_b32_e32 v248, 16, v228
	v_and_b32_e32 v249, 0xffff0000, v228
	v_lshlrev_b32_e32 v250, 16, v229
	v_and_b32_e32 v251, 0xffff0000, v229
	v_max_f32_e32 v244, 0x38d1b717, v244
	v_max_f32_e32 v245, 0x38d1b717, v245
	v_max_f32_e32 v246, 0x38d1b717, v246
	v_max_f32_e32 v247, 0x38d1b717, v247
	v_max_f32_e32 v248, 0x38d1b717, v248
	v_max_f32_e32 v249, 0x38d1b717, v249
	v_max_f32_e32 v250, 0x38d1b717, v250
	v_max_f32_e32 v251, 0x38d1b717, v251
;     __device__ __forceinline__ bool apply(f32x4 (&acc)[2][2][4][2], const pg8::Unit& u, int wr, int wc, int fr, int fq) const {
;     ...
;         const int row0 = u.pm * 256 + wr * 64 + fr, colb = u.pn * 256 + wc * 32 + 8 * fq, br = u.br;
;         const bf16_t* G = (const bf16_t*)(ws + WS_GATE); bf16_t* Mb = (bf16_t*)(ws + WS_HB);
; #pragma unroll
;         for (int ai = 0; ai < 2; ++ai)
; #pragma unroll
;             for (int m = 0; m < 4; ++m)
; #pragma unroll
;                 for (int bj = 0; bj < 2; ++bj) { const int row = row0 + ai * 128 + m * 16, col0 = colb + bj * 128;
;                     float gc[8], gn[8]; load8(G + (size_t)row * GT_COLS + br * 1024 + col0, gc);
;                     if (br < 2) load8(G + (size_t)row * GT_COLS + (br + 1) * 1024 + col0, gn);
;                     else {
; #pragma unroll
;                         for (int j = 0; j < 8; ++j) gn[j] = 1.f; }
;                     float v[8]; const f32x4 v0 = acc[ai][bj][m][0], v1 = acc[ai][bj][m][1];
;                     v[0] = v0.x; v[1] = v0.y; v[2] = v0.z; v[3] = v0.w; v[4] = v1.x; v[5] = v1.y; v[6] = v1.z; v[7] = v1.w;
; #pragma unroll
;                     for (int j = 0; j < 8; ++j) v[j] *= fmaxf(gc[j], 1e-4f);
;                     if (br == 2) store8(Mb + (size_t)row * 1024 + col0, v);
;                     else {
; #pragma unroll
;                         for (int j = 0; j < 8; ++j) v[j] *= __builtin_amdgcn_rcpf(fmaxf(gn[j], 1e-4f));
;                         acc[ai][bj][m][0] = (f32x4){v[0], v[1], v[2], v[3]}; acc[ai][bj][m][1] = (f32x4){v[4], v[5], v[6], v[7]}; }
;                 }
;         return br < 2;
	v_pk_mul_f32 v[112:113], v[112:113], v[244:245]
	v_pk_mul_f32 v[114:115], v[114:115], v[246:247]
	v_pk_mul_f32 v[108:109], v[108:109], v[248:249]
	v_pk_mul_f32 v[110:111], v[110:111], v[250:251]
	v_lshlrev_b32_e32 v244, 16, v230
	v_and_b32_e32 v245, 0xffff0000, v230
	v_lshlrev_b32_e32 v246, 16, v231
	v_and_b32_e32 v247, 0xffff0000, v231
	v_lshlrev_b32_e32 v248, 16, v232
	v_and_b32_e32 v249, 0xffff0000, v232
	v_lshlrev_b32_e32 v250, 16, v233
	v_and_b32_e32 v251, 0xffff0000, v233
	v_max_f32_e32 v244, 0x38d1b717, v244
	v_max_f32_e32 v245, 0x38d1b717, v245
	v_max_f32_e32 v246, 0x38d1b717, v246
	v_max_f32_e32 v247, 0x38d1b717, v247
	v_max_f32_e32 v248, 0x38d1b717, v248
	v_max_f32_e32 v249, 0x38d1b717, v249
	v_max_f32_e32 v250, 0x38d1b717, v250
	v_max_f32_e32 v251, 0x38d1b717, v251
	v_rcp_f32_e32 v244, v244
	v_rcp_f32_e32 v245, v245
	v_rcp_f32_e32 v246, v246
	v_rcp_f32_e32 v247, v247
	v_rcp_f32_e32 v248, v248
	v_rcp_f32_e32 v249, v249
	v_rcp_f32_e32 v250, v250
	v_rcp_f32_e32 v251, v251
	s_nop 0
	v_pk_mul_f32 v[112:113], v[112:113], v[244:245]
	v_pk_mul_f32 v[114:115], v[114:115], v[246:247]
	v_pk_mul_f32 v[108:109], v[108:109], v[248:249]
	v_pk_mul_f32 v[110:111], v[110:111], v[250:251]
	v_lshlrev_b32_e32 v244, 16, v234
	v_and_b32_e32 v245, 0xffff0000, v234
	v_lshlrev_b32_e32 v246, 16, v235
	v_and_b32_e32 v247, 0xffff0000, v235
	v_lshlrev_b32_e32 v248, 16, v236
	v_and_b32_e32 v249, 0xffff0000, v236
	v_lshlrev_b32_e32 v250, 16, v237
	v_and_b32_e32 v251, 0xffff0000, v237
	v_max_f32_e32 v244, 0x38d1b717, v244
	v_max_f32_e32 v245, 0x38d1b717, v245
	v_max_f32_e32 v246, 0x38d1b717, v246
	v_max_f32_e32 v247, 0x38d1b717, v247
	v_max_f32_e32 v248, 0x38d1b717, v248
	v_max_f32_e32 v249, 0x38d1b717, v249
	v_max_f32_e32 v250, 0x38d1b717, v250
	v_max_f32_e32 v251, 0x38d1b717, v251
	v_pk_mul_f32 v[104:105], v[104:105], v[244:245]
	v_pk_mul_f32 v[106:107], v[106:107], v[246:247]
	v_pk_mul_f32 v[100:101], v[100:101], v[248:249]
	v_pk_mul_f32 v[102:103], v[102:103], v[250:251]
	v_lshlrev_b32_e32 v244, 16, v238
	v_and_b32_e32 v245, 0xffff0000, v238
	v_lshlrev_b32_e32 v246, 16, v239
	v_and_b32_e32 v247, 0xffff0000, v239
	v_lshlrev_b32_e32 v248, 16, v240
	v_and_b32_e32 v249, 0xffff0000, v240
	v_lshlrev_b32_e32 v250, 16, v241
	v_and_b32_e32 v251, 0xffff0000, v241
	v_max_f32_e32 v244, 0x38d1b717, v244
	v_max_f32_e32 v245, 0x38d1b717, v245
	v_max_f32_e32 v246, 0x38d1b717, v246
	v_max_f32_e32 v247, 0x38d1b717, v247
	v_max_f32_e32 v248, 0x38d1b717, v248
	v_max_f32_e32 v249, 0x38d1b717, v249
	v_max_f32_e32 v250, 0x38d1b717, v250
	v_max_f32_e32 v251, 0x38d1b717, v251
	v_rcp_f32_e32 v244, v244
	v_rcp_f32_e32 v245, v245
	v_rcp_f32_e32 v246, v246
	v_rcp_f32_e32 v247, v247
	v_rcp_f32_e32 v248, v248
	v_rcp_f32_e32 v249, v249
	v_rcp_f32_e32 v250, v250
	v_rcp_f32_e32 v251, v251
	s_nop 0
	v_pk_mul_f32 v[104:105], v[104:105], v[244:245]
	v_pk_mul_f32 v[106:107], v[106:107], v[246:247]
	v_pk_mul_f32 v[100:101], v[100:101], v[248:249]
	v_pk_mul_f32 v[102:103], v[102:103], v[250:251]
	global_load_dwordx4 v[210:213], v190, s[4:5]
	global_load_dwordx4 v[214:217], v190, s[4:5] offset:2048
	global_load_dwordx4 v[218:221], v190, s[4:5] offset:256
	global_load_dwordx4 v[222:225], v190, s[4:5] offset:2304
	global_load_dwordx4 v[226:229], v191, s[4:5]
	global_load_dwordx4 v[230:233], v191, s[4:5] offset:2048
	global_load_dwordx4 v[234:237], v191, s[4:5] offset:256
	global_load_dwordx4 v[238:241], v191, s[4:5] offset:2304
	s_waitcnt vmcnt(8)
	v_lshlrev_b32_e32 v244, 16, v132
	v_and_b32_e32 v245, 0xffff0000, v132
	v_lshlrev_b32_e32 v246, 16, v133
	v_and_b32_e32 v247, 0xffff0000, v133
	v_lshlrev_b32_e32 v248, 16, v134
	v_and_b32_e32 v249, 0xffff0000, v134
	v_lshlrev_b32_e32 v250, 16, v135
	v_and_b32_e32 v251, 0xffff0000, v135
	v_max_f32_e32 v244, 0x38d1b717, v244
	v_max_f32_e32 v245, 0x38d1b717, v245
	v_max_f32_e32 v246, 0x38d1b717, v246
	v_max_f32_e32 v247, 0x38d1b717, v247
	v_max_f32_e32 v248, 0x38d1b717, v248
	v_max_f32_e32 v249, 0x38d1b717, v249
	v_max_f32_e32 v250, 0x38d1b717, v250
	v_max_f32_e32 v251, 0x38d1b717, v251
	v_pk_mul_f32 v[96:97], v[96:97], v[244:245]
	v_pk_mul_f32 v[98:99], v[98:99], v[246:247]
	v_pk_mul_f32 v[92:93], v[92:93], v[248:249]
	v_pk_mul_f32 v[94:95], v[94:95], v[250:251]
	v_lshlrev_b32_e32 v244, 16, v136
	v_and_b32_e32 v245, 0xffff0000, v136
	v_lshlrev_b32_e32 v246, 16, v137
	v_and_b32_e32 v247, 0xffff0000, v137
	v_lshlrev_b32_e32 v248, 16, v138
	v_and_b32_e32 v249, 0xffff0000, v138
	v_lshlrev_b32_e32 v250, 16, v139
	v_and_b32_e32 v251, 0xffff0000, v139
	v_max_f32_e32 v244, 0x38d1b717, v244
	v_max_f32_e32 v245, 0x38d1b717, v245
	v_max_f32_e32 v246, 0x38d1b717, v246
	v_max_f32_e32 v247, 0x38d1b717, v247
	v_max_f32_e32 v248, 0x38d1b717, v248
	v_max_f32_e32 v249, 0x38d1b717, v249
	v_max_f32_e32 v250, 0x38d1b717, v250
	v_max_f32_e32 v251, 0x38d1b717, v251
	v_rcp_f32_e32 v244, v244
	v_rcp_f32_e32 v245, v245
	v_rcp_f32_e32 v246, v246
	v_rcp_f32_e32 v247, v247
	v_rcp_f32_e32 v248, v248
	v_rcp_f32_e32 v249, v249
	v_rcp_f32_e32 v250, v250
	v_rcp_f32_e32 v251, v251
	s_nop 0
	v_pk_mul_f32 v[96:97], v[96:97], v[244:245]
	v_pk_mul_f32 v[98:99], v[98:99], v[246:247]
	v_pk_mul_f32 v[92:93], v[92:93], v[248:249]
	v_pk_mul_f32 v[94:95], v[94:95], v[250:251]
	v_lshlrev_b32_e32 v244, 16, v140
	v_and_b32_e32 v245, 0xffff0000, v140
	v_lshlrev_b32_e32 v246, 16, v141
	v_and_b32_e32 v247, 0xffff0000, v141
	v_lshlrev_b32_e32 v248, 16, v142
	v_and_b32_e32 v249, 0xffff0000, v142
	v_lshlrev_b32_e32 v250, 16, v143
	v_and_b32_e32 v251, 0xffff0000, v143
	v_max_f32_e32 v244, 0x38d1b717, v244
	v_max_f32_e32 v245, 0x38d1b717, v245
	v_max_f32_e32 v246, 0x38d1b717, v246
	v_max_f32_e32 v247, 0x38d1b717, v247
;     __device__ __forceinline__ bool apply(f32x4 (&acc)[2][2][4][2], const pg8::Unit& u, int wr, int wc, int fr, int fq) const {
;     ...
;         const int row0 = u.pm * 256 + wr * 64 + fr, colb = u.pn * 256 + wc * 32 + 8 * fq, br = u.br;
;         const bf16_t* G = (const bf16_t*)(ws + WS_GATE); bf16_t* Mb = (bf16_t*)(ws + WS_HB);
; #pragma unroll
;         for (int ai = 0; ai < 2; ++ai)
; #pragma unroll
;             for (int m = 0; m < 4; ++m)
; #pragma unroll
;                 for (int bj = 0; bj < 2; ++bj) { const int row = row0 + ai * 128 + m * 16, col0 = colb + bj * 128;
;                     float gc[8], gn[8]; load8(G + (size_t)row * GT_COLS + br * 1024 + col0, gc);
;                     if (br < 2) load8(G + (size_t)row * GT_COLS + (br + 1) * 1024 + col0, gn);
;                     else {
; #pragma unroll
;                         for (int j = 0; j < 8; ++j) gn[j] = 1.f; }
;                     float v[8]; const f32x4 v0 = acc[ai][bj][m][0], v1 = acc[ai][bj][m][1];
;                     v[0] = v0.x; v[1] = v0.y; v[2] = v0.z; v[3] = v0.w; v[4] = v1.x; v[5] = v1.y; v[6] = v1.z; v[7] = v1.w;
; #pragma unroll
;                     for (int j = 0; j < 8; ++j) v[j] *= fmaxf(gc[j], 1e-4f);
;                     if (br == 2) store8(Mb + (size_t)row * 1024 + col0, v);
;                     else {
; #pragma unroll
;                         for (int j = 0; j < 8; ++j) v[j] *= __builtin_amdgcn_rcpf(fmaxf(gn[j], 1e-4f));
;                         acc[ai][bj][m][0] = (f32x4){v[0], v[1], v[2], v[3]}; acc[ai][bj][m][1] = (f32x4){v[4], v[5], v[6], v[7]}; }
;                 }
;         return br < 2;
	v_max_f32_e32 v248, 0x38d1b717, v248
	v_max_f32_e32 v249, 0x38d1b717, v249
	v_max_f32_e32 v250, 0x38d1b717, v250
	v_max_f32_e32 v251, 0x38d1b717, v251
	v_pk_mul_f32 v[88:89], v[88:89], v[244:245]
	v_pk_mul_f32 v[90:91], v[90:91], v[246:247]
	v_pk_mul_f32 v[84:85], v[84:85], v[248:249]
	v_pk_mul_f32 v[86:87], v[86:87], v[250:251]
	v_lshlrev_b32_e32 v244, 16, v144
	v_and_b32_e32 v245, 0xffff0000, v144
	v_lshlrev_b32_e32 v246, 16, v145
	v_and_b32_e32 v247, 0xffff0000, v145
	v_lshlrev_b32_e32 v248, 16, v146
	v_and_b32_e32 v249, 0xffff0000, v146
	v_lshlrev_b32_e32 v250, 16, v147
	v_and_b32_e32 v251, 0xffff0000, v147
	v_max_f32_e32 v244, 0x38d1b717, v244
	v_max_f32_e32 v245, 0x38d1b717, v245
	v_max_f32_e32 v246, 0x38d1b717, v246
	v_max_f32_e32 v247, 0x38d1b717, v247
	v_max_f32_e32 v248, 0x38d1b717, v248
	v_max_f32_e32 v249, 0x38d1b717, v249
	v_max_f32_e32 v250, 0x38d1b717, v250
	v_max_f32_e32 v251, 0x38d1b717, v251
	v_rcp_f32_e32 v244, v244
	v_rcp_f32_e32 v245, v245
	v_rcp_f32_e32 v246, v246
	v_rcp_f32_e32 v247, v247
	v_rcp_f32_e32 v248, v248
	v_rcp_f32_e32 v249, v249
	v_rcp_f32_e32 v250, v250
	v_rcp_f32_e32 v251, v251
	s_nop 0
	v_pk_mul_f32 v[88:89], v[88:89], v[244:245]
	v_pk_mul_f32 v[90:91], v[90:91], v[246:247]
	v_pk_mul_f32 v[84:85], v[84:85], v[248:249]
	v_pk_mul_f32 v[86:87], v[86:87], v[250:251]
	v_lshlrev_b32_e32 v244, 16, v148
	v_and_b32_e32 v245, 0xffff0000, v148
	v_lshlrev_b32_e32 v246, 16, v149
	v_and_b32_e32 v247, 0xffff0000, v149
	v_lshlrev_b32_e32 v248, 16, v150
	v_and_b32_e32 v249, 0xffff0000, v150
	v_lshlrev_b32_e32 v250, 16, v151
	v_and_b32_e32 v251, 0xffff0000, v151
	v_max_f32_e32 v244, 0x38d1b717, v244
	v_max_f32_e32 v245, 0x38d1b717, v245
	v_max_f32_e32 v246, 0x38d1b717, v246
	v_max_f32_e32 v247, 0x38d1b717, v247
	v_max_f32_e32 v248, 0x38d1b717, v248
	v_max_f32_e32 v249, 0x38d1b717, v249
	v_max_f32_e32 v250, 0x38d1b717, v250
	v_max_f32_e32 v251, 0x38d1b717, v251
	v_pk_mul_f32 v[80:81], v[80:81], v[244:245]
	v_pk_mul_f32 v[82:83], v[82:83], v[246:247]
	v_pk_mul_f32 v[76:77], v[76:77], v[248:249]
	v_pk_mul_f32 v[78:79], v[78:79], v[250:251]
	v_lshlrev_b32_e32 v244, 16, v152
	v_and_b32_e32 v245, 0xffff0000, v152
	v_lshlrev_b32_e32 v246, 16, v153
	v_and_b32_e32 v247, 0xffff0000, v153
	v_lshlrev_b32_e32 v248, 16, v154
	v_and_b32_e32 v249, 0xffff0000, v154
	v_lshlrev_b32_e32 v250, 16, v155
	v_and_b32_e32 v251, 0xffff0000, v155
	v_max_f32_e32 v244, 0x38d1b717, v244
	v_max_f32_e32 v245, 0x38d1b717, v245
	v_max_f32_e32 v246, 0x38d1b717, v246
	v_max_f32_e32 v247, 0x38d1b717, v247
	v_max_f32_e32 v248, 0x38d1b717, v248
	v_max_f32_e32 v249, 0x38d1b717, v249
	v_max_f32_e32 v250, 0x38d1b717, v250
	v_max_f32_e32 v251, 0x38d1b717, v251
	v_rcp_f32_e32 v244, v244
	v_rcp_f32_e32 v245, v245
	v_rcp_f32_e32 v246, v246
	v_rcp_f32_e32 v247, v247
	v_rcp_f32_e32 v248, v248
	v_rcp_f32_e32 v249, v249
	v_rcp_f32_e32 v250, v250
	v_rcp_f32_e32 v251, v251
	s_nop 0
	v_pk_mul_f32 v[80:81], v[80:81], v[244:245]
	v_pk_mul_f32 v[82:83], v[82:83], v[246:247]
	v_pk_mul_f32 v[76:77], v[76:77], v[248:249]
	v_pk_mul_f32 v[78:79], v[78:79], v[250:251]
	v_lshlrev_b32_e32 v244, 16, v156
	v_and_b32_e32 v245, 0xffff0000, v156
	v_lshlrev_b32_e32 v246, 16, v157
	v_and_b32_e32 v247, 0xffff0000, v157
	v_lshlrev_b32_e32 v248, 16, v158
	v_and_b32_e32 v249, 0xffff0000, v158
	v_lshlrev_b32_e32 v250, 16, v159
	v_and_b32_e32 v251, 0xffff0000, v159
	v_max_f32_e32 v244, 0x38d1b717, v244
	v_max_f32_e32 v245, 0x38d1b717, v245
	v_max_f32_e32 v246, 0x38d1b717, v246
	v_max_f32_e32 v247, 0x38d1b717, v247
	v_max_f32_e32 v248, 0x38d1b717, v248
	v_max_f32_e32 v249, 0x38d1b717, v249
	v_max_f32_e32 v250, 0x38d1b717, v250
	v_max_f32_e32 v251, 0x38d1b717, v251
	v_pk_mul_f32 v[72:73], v[72:73], v[244:245]
	v_pk_mul_f32 v[74:75], v[74:75], v[246:247]
	v_pk_mul_f32 v[68:69], v[68:69], v[248:249]
	v_pk_mul_f32 v[70:71], v[70:71], v[250:251]
	v_lshlrev_b32_e32 v244, 16, v160
	v_and_b32_e32 v245, 0xffff0000, v160
	v_lshlrev_b32_e32 v246, 16, v161
	v_and_b32_e32 v247, 0xffff0000, v161
	v_lshlrev_b32_e32 v248, 16, v162
	v_and_b32_e32 v249, 0xffff0000, v162
	v_lshlrev_b32_e32 v250, 16, v163
	v_and_b32_e32 v251, 0xffff0000, v163
	v_max_f32_e32 v244, 0x38d1b717, v244
	v_max_f32_e32 v245, 0x38d1b717, v245
	v_max_f32_e32 v246, 0x38d1b717, v246
	v_max_f32_e32 v247, 0x38d1b717, v247
	v_max_f32_e32 v248, 0x38d1b717, v248
	v_max_f32_e32 v249, 0x38d1b717, v249
	v_max_f32_e32 v250, 0x38d1b717, v250
	v_max_f32_e32 v251, 0x38d1b717, v251
	v_rcp_f32_e32 v244, v244
	v_rcp_f32_e32 v245, v245
	v_rcp_f32_e32 v246, v246
	v_rcp_f32_e32 v247, v247
	v_rcp_f32_e32 v248, v248
	v_rcp_f32_e32 v249, v249
	v_rcp_f32_e32 v250, v250
	v_rcp_f32_e32 v251, v251
	s_nop 0
	v_pk_mul_f32 v[72:73], v[72:73], v[244:245]
	v_pk_mul_f32 v[74:75], v[74:75], v[246:247]
	v_pk_mul_f32 v[68:69], v[68:69], v[248:249]
	v_pk_mul_f32 v[70:71], v[70:71], v[250:251]
	global_load_dwordx4 v[132:135], v200, s[4:5]
	global_load_dwordx4 v[136:139], v200, s[4:5] offset:2048
	global_load_dwordx4 v[140:143], v200, s[4:5] offset:256
	global_load_dwordx4 v[144:147], v200, s[4:5] offset:2304
	global_load_dwordx4 v[148:151], v201, s[4:5]
	global_load_dwordx4 v[152:155], v201, s[4:5] offset:2048
	global_load_dwordx4 v[156:159], v201, s[4:5] offset:256
	global_load_dwordx4 v[160:163], v201, s[4:5] offset:2304
	s_waitcnt vmcnt(8)
;     __device__ __forceinline__ bool apply(f32x4 (&acc)[2][2][4][2], const pg8::Unit& u, int wr, int wc, int fr, int fq) const {
;     ...
;         const int row0 = u.pm * 256 + wr * 64 + fr, colb = u.pn * 256 + wc * 32 + 8 * fq, br = u.br;
;         const bf16_t* G = (const bf16_t*)(ws + WS_GATE); bf16_t* Mb = (bf16_t*)(ws + WS_HB);
; #pragma unroll
;         for (int ai = 0; ai < 2; ++ai)
; #pragma unroll
;             for (int m = 0; m < 4; ++m)
; #pragma unroll
;                 for (int bj = 0; bj < 2; ++bj) { const int row = row0 + ai * 128 + m * 16, col0 = colb + bj * 128;
;                     float gc[8], gn[8]; load8(G + (size_t)row * GT_COLS + br * 1024 + col0, gc);
;                     if (br < 2) load8(G + (size_t)row * GT_COLS + (br + 1) * 1024 + col0, gn);
;                     else {
; #pragma unroll
;                         for (int j = 0; j < 8; ++j) gn[j] = 1.f; }
;                     float v[8]; const f32x4 v0 = acc[ai][bj][m][0], v1 = acc[ai][bj][m][1];
;                     v[0] = v0.x; v[1] = v0.y; v[2] = v0.z; v[3] = v0.w; v[4] = v1.x; v[5] = v1.y; v[6] = v1.z; v[7] = v1.w;
; #pragma unroll
;                     for (int j = 0; j < 8; ++j) v[j] *= fmaxf(gc[j], 1e-4f);
;                     if (br == 2) store8(Mb + (size_t)row * 1024 + col0, v);
;                     else {
; #pragma unroll
;                         for (int j = 0; j < 8; ++j) v[j] *= __builtin_amdgcn_rcpf(fmaxf(gn[j], 1e-4f));
;                         acc[ai][bj][m][0] = (f32x4){v[0], v[1], v[2], v[3]}; acc[ai][bj][m][1] = (f32x4){v[4], v[5], v[6], v[7]}; }
;                 }
;         return br < 2;
	v_lshlrev_b32_e32 v244, 16, v210
	v_and_b32_e32 v245, 0xffff0000, v210
	v_lshlrev_b32_e32 v246, 16, v211
	v_and_b32_e32 v247, 0xffff0000, v211
	v_lshlrev_b32_e32 v248, 16, v212
	v_and_b32_e32 v249, 0xffff0000, v212
	v_lshlrev_b32_e32 v250, 16, v213
	v_and_b32_e32 v251, 0xffff0000, v213
	v_max_f32_e32 v244, 0x38d1b717, v244
	v_max_f32_e32 v245, 0x38d1b717, v245
	v_max_f32_e32 v246, 0x38d1b717, v246
	v_max_f32_e32 v247, 0x38d1b717, v247
	v_max_f32_e32 v248, 0x38d1b717, v248
	v_max_f32_e32 v249, 0x38d1b717, v249
	v_max_f32_e32 v250, 0x38d1b717, v250
	v_max_f32_e32 v251, 0x38d1b717, v251
	v_pk_mul_f32 v[64:65], v[64:65], v[244:245]
	v_pk_mul_f32 v[66:67], v[66:67], v[246:247]
	v_pk_mul_f32 v[60:61], v[60:61], v[248:249]
	v_pk_mul_f32 v[62:63], v[62:63], v[250:251]
	v_lshlrev_b32_e32 v244, 16, v214
	v_and_b32_e32 v245, 0xffff0000, v214
	v_lshlrev_b32_e32 v246, 16, v215
	v_and_b32_e32 v247, 0xffff0000, v215
	v_lshlrev_b32_e32 v248, 16, v216
	v_and_b32_e32 v249, 0xffff0000, v216
	v_lshlrev_b32_e32 v250, 16, v217
	v_and_b32_e32 v251, 0xffff0000, v217
	v_max_f32_e32 v244, 0x38d1b717, v244
	v_max_f32_e32 v245, 0x38d1b717, v245
	v_max_f32_e32 v246, 0x38d1b717, v246
	v_max_f32_e32 v247, 0x38d1b717, v247
	v_max_f32_e32 v248, 0x38d1b717, v248
	v_max_f32_e32 v249, 0x38d1b717, v249
	v_max_f32_e32 v250, 0x38d1b717, v250
	v_max_f32_e32 v251, 0x38d1b717, v251
	v_rcp_f32_e32 v244, v244
	v_rcp_f32_e32 v245, v245
	v_rcp_f32_e32 v246, v246
	v_rcp_f32_e32 v247, v247
	v_rcp_f32_e32 v248, v248
	v_rcp_f32_e32 v249, v249
	v_rcp_f32_e32 v250, v250
	v_rcp_f32_e32 v251, v251
	s_nop 0
	v_pk_mul_f32 v[64:65], v[64:65], v[244:245]
	v_pk_mul_f32 v[66:67], v[66:67], v[246:247]
	v_pk_mul_f32 v[60:61], v[60:61], v[248:249]
	v_pk_mul_f32 v[62:63], v[62:63], v[250:251]
	v_lshlrev_b32_e32 v244, 16, v218
	v_and_b32_e32 v245, 0xffff0000, v218
	v_lshlrev_b32_e32 v246, 16, v219
	v_and_b32_e32 v247, 0xffff0000, v219
	v_lshlrev_b32_e32 v248, 16, v220
	v_and_b32_e32 v249, 0xffff0000, v220
	v_lshlrev_b32_e32 v250, 16, v221
	v_and_b32_e32 v251, 0xffff0000, v221
	v_max_f32_e32 v244, 0x38d1b717, v244
	v_max_f32_e32 v245, 0x38d1b717, v245
	v_max_f32_e32 v246, 0x38d1b717, v246
	v_max_f32_e32 v247, 0x38d1b717, v247
	v_max_f32_e32 v248, 0x38d1b717, v248
	v_max_f32_e32 v249, 0x38d1b717, v249
	v_max_f32_e32 v250, 0x38d1b717, v250
	v_max_f32_e32 v251, 0x38d1b717, v251
	v_pk_mul_f32 v[56:57], v[56:57], v[244:245]
	v_pk_mul_f32 v[58:59], v[58:59], v[246:247]
	v_pk_mul_f32 v[52:53], v[52:53], v[248:249]
	v_pk_mul_f32 v[54:55], v[54:55], v[250:251]
	v_lshlrev_b32_e32 v244, 16, v222
	v_and_b32_e32 v245, 0xffff0000, v222
	v_lshlrev_b32_e32 v246, 16, v223
	v_and_b32_e32 v247, 0xffff0000, v223
	v_lshlrev_b32_e32 v248, 16, v224
	v_and_b32_e32 v249, 0xffff0000, v224
	v_lshlrev_b32_e32 v250, 16, v225
	v_and_b32_e32 v251, 0xffff0000, v225
	v_max_f32_e32 v244, 0x38d1b717, v244
	v_max_f32_e32 v245, 0x38d1b717, v245
	v_max_f32_e32 v246, 0x38d1b717, v246
	v_max_f32_e32 v247, 0x38d1b717, v247
	v_max_f32_e32 v248, 0x38d1b717, v248
	v_max_f32_e32 v249, 0x38d1b717, v249
	v_max_f32_e32 v250, 0x38d1b717, v250
	v_max_f32_e32 v251, 0x38d1b717, v251
	v_rcp_f32_e32 v244, v244
	v_rcp_f32_e32 v245, v245
	v_rcp_f32_e32 v246, v246
	v_rcp_f32_e32 v247, v247
	v_rcp_f32_e32 v248, v248
	v_rcp_f32_e32 v249, v249
	v_rcp_f32_e32 v250, v250
	v_rcp_f32_e32 v251, v251
	s_nop 0
	v_pk_mul_f32 v[56:57], v[56:57], v[244:245]
	v_pk_mul_f32 v[58:59], v[58:59], v[246:247]
	v_pk_mul_f32 v[52:53], v[52:53], v[248:249]
	v_pk_mul_f32 v[54:55], v[54:55], v[250:251]
	v_lshlrev_b32_e32 v244, 16, v226
	v_and_b32_e32 v245, 0xffff0000, v226
	v_lshlrev_b32_e32 v246, 16, v227
	v_and_b32_e32 v247, 0xffff0000, v227
	v_lshlrev_b32_e32 v248, 16, v228
	v_and_b32_e32 v249, 0xffff0000, v228
	v_lshlrev_b32_e32 v250, 16, v229
	v_and_b32_e32 v251, 0xffff0000, v229
	v_max_f32_e32 v244, 0x38d1b717, v244
	v_max_f32_e32 v245, 0x38d1b717, v245
	v_max_f32_e32 v246, 0x38d1b717, v246
	v_max_f32_e32 v247, 0x38d1b717, v247
	v_max_f32_e32 v248, 0x38d1b717, v248
	v_max_f32_e32 v249, 0x38d1b717, v249
	v_max_f32_e32 v250, 0x38d1b717, v250
	v_max_f32_e32 v251, 0x38d1b717, v251
	v_pk_mul_f32 v[48:49], v[48:49], v[244:245]
	v_pk_mul_f32 v[50:51], v[50:51], v[246:247]
	v_pk_mul_f32 v[44:45], v[44:45], v[248:249]
	v_pk_mul_f32 v[46:47], v[46:47], v[250:251]
	v_lshlrev_b32_e32 v244, 16, v230
	v_and_b32_e32 v245, 0xffff0000, v230
	v_lshlrev_b32_e32 v246, 16, v231
	v_and_b32_e32 v247, 0xffff0000, v231
	v_lshlrev_b32_e32 v248, 16, v232
	v_and_b32_e32 v249, 0xffff0000, v232
	v_lshlrev_b32_e32 v250, 16, v233
	v_and_b32_e32 v251, 0xffff0000, v233
	v_max_f32_e32 v244, 0x38d1b717, v244
	v_max_f32_e32 v245, 0x38d1b717, v245
	v_max_f32_e32 v246, 0x38d1b717, v246
	v_max_f32_e32 v247, 0x38d1b717, v247
	v_max_f32_e32 v248, 0x38d1b717, v248
	v_max_f32_e32 v249, 0x38d1b717, v249
	v_max_f32_e32 v250, 0x38d1b717, v250
	v_max_f32_e32 v251, 0x38d1b717, v251
	v_rcp_f32_e32 v244, v244
	v_rcp_f32_e32 v245, v245
	v_rcp_f32_e32 v246, v246
	v_rcp_f32_e32 v247, v247
	v_rcp_f32_e32 v248, v248
	v_rcp_f32_e32 v249, v249
	v_rcp_f32_e32 v250, v250
	v_rcp_f32_e32 v251, v251
	s_nop 0
	v_pk_mul_f32 v[48:49], v[48:49], v[244:245]
	v_pk_mul_f32 v[50:51], v[50:51], v[246:247]
	v_pk_mul_f32 v[44:45], v[44:45], v[248:249]
	v_pk_mul_f32 v[46:47], v[46:47], v[250:251]
	v_lshlrev_b32_e32 v244, 16, v234
	v_and_b32_e32 v245, 0xffff0000, v234
	v_lshlrev_b32_e32 v246, 16, v235
	v_and_b32_e32 v247, 0xffff0000, v235
	v_lshlrev_b32_e32 v248, 16, v236
	v_and_b32_e32 v249, 0xffff0000, v236
	v_lshlrev_b32_e32 v250, 16, v237
	v_and_b32_e32 v251, 0xffff0000, v237
	v_max_f32_e32 v244, 0x38d1b717, v244
	v_max_f32_e32 v245, 0x38d1b717, v245
;     __device__ __forceinline__ bool apply(f32x4 (&acc)[2][2][4][2], const pg8::Unit& u, int wr, int wc, int fr, int fq) const {
;     ...
;         const int row0 = u.pm * 256 + wr * 64 + fr, colb = u.pn * 256 + wc * 32 + 8 * fq, br = u.br;
;         const bf16_t* G = (const bf16_t*)(ws + WS_GATE); bf16_t* Mb = (bf16_t*)(ws + WS_HB);
; #pragma unroll
;         for (int ai = 0; ai < 2; ++ai)
; #pragma unroll
;             for (int m = 0; m < 4; ++m)
; #pragma unroll
;                 for (int bj = 0; bj < 2; ++bj) { const int row = row0 + ai * 128 + m * 16, col0 = colb + bj * 128;
;                     float gc[8], gn[8]; load8(G + (size_t)row * GT_COLS + br * 1024 + col0, gc);
;                     if (br < 2) load8(G + (size_t)row * GT_COLS + (br + 1) * 1024 + col0, gn);
;                     else {
; #pragma unroll
;                         for (int j = 0; j < 8; ++j) gn[j] = 1.f; }
;                     float v[8]; const f32x4 v0 = acc[ai][bj][m][0], v1 = acc[ai][bj][m][1];
;                     v[0] = v0.x; v[1] = v0.y; v[2] = v0.z; v[3] = v0.w; v[4] = v1.x; v[5] = v1.y; v[6] = v1.z; v[7] = v1.w;
; #pragma unroll
;                     for (int j = 0; j < 8; ++j) v[j] *= fmaxf(gc[j], 1e-4f);
;                     if (br == 2) store8(Mb + (size_t)row * 1024 + col0, v);
;                     else {
; #pragma unroll
;                         for (int j = 0; j < 8; ++j) v[j] *= __builtin_amdgcn_rcpf(fmaxf(gn[j], 1e-4f));
;                         acc[ai][bj][m][0] = (f32x4){v[0], v[1], v[2], v[3]}; acc[ai][bj][m][1] = (f32x4){v[4], v[5], v[6], v[7]}; }
;                 }
;         return br < 2;
	v_max_f32_e32 v246, 0x38d1b717, v246
	v_max_f32_e32 v247, 0x38d1b717, v247
	v_max_f32_e32 v248, 0x38d1b717, v248
	v_max_f32_e32 v249, 0x38d1b717, v249
	v_max_f32_e32 v250, 0x38d1b717, v250
	v_max_f32_e32 v251, 0x38d1b717, v251
	v_pk_mul_f32 v[40:41], v[40:41], v[244:245]
	v_pk_mul_f32 v[42:43], v[42:43], v[246:247]
	v_pk_mul_f32 v[36:37], v[36:37], v[248:249]
	v_pk_mul_f32 v[38:39], v[38:39], v[250:251]
	v_lshlrev_b32_e32 v244, 16, v238
	v_and_b32_e32 v245, 0xffff0000, v238
	v_lshlrev_b32_e32 v246, 16, v239
	v_and_b32_e32 v247, 0xffff0000, v239
	v_lshlrev_b32_e32 v248, 16, v240
	v_and_b32_e32 v249, 0xffff0000, v240
	v_lshlrev_b32_e32 v250, 16, v241
	v_and_b32_e32 v251, 0xffff0000, v241
	v_max_f32_e32 v244, 0x38d1b717, v244
	v_max_f32_e32 v245, 0x38d1b717, v245
	v_max_f32_e32 v246, 0x38d1b717, v246
	v_max_f32_e32 v247, 0x38d1b717, v247
	v_max_f32_e32 v248, 0x38d1b717, v248
	v_max_f32_e32 v249, 0x38d1b717, v249
	v_max_f32_e32 v250, 0x38d1b717, v250
	v_max_f32_e32 v251, 0x38d1b717, v251
	v_rcp_f32_e32 v244, v244
	v_rcp_f32_e32 v245, v245
	v_rcp_f32_e32 v246, v246
	v_rcp_f32_e32 v247, v247
	v_rcp_f32_e32 v248, v248
	v_rcp_f32_e32 v249, v249
	v_rcp_f32_e32 v250, v250
	v_rcp_f32_e32 v251, v251
	s_nop 0
	v_pk_mul_f32 v[40:41], v[40:41], v[244:245]
	v_pk_mul_f32 v[42:43], v[42:43], v[246:247]
	v_pk_mul_f32 v[36:37], v[36:37], v[248:249]
	v_pk_mul_f32 v[38:39], v[38:39], v[250:251]
	s_waitcnt vmcnt(0)
	v_lshlrev_b32_e32 v244, 16, v132
	v_and_b32_e32 v245, 0xffff0000, v132
	v_lshlrev_b32_e32 v246, 16, v133
	v_and_b32_e32 v247, 0xffff0000, v133
	v_lshlrev_b32_e32 v248, 16, v134
	v_and_b32_e32 v249, 0xffff0000, v134
	v_lshlrev_b32_e32 v250, 16, v135
	v_and_b32_e32 v251, 0xffff0000, v135
	v_max_f32_e32 v244, 0x38d1b717, v244
	v_max_f32_e32 v245, 0x38d1b717, v245
	v_max_f32_e32 v246, 0x38d1b717, v246
	v_max_f32_e32 v247, 0x38d1b717, v247
	v_max_f32_e32 v248, 0x38d1b717, v248
	v_max_f32_e32 v249, 0x38d1b717, v249
	v_max_f32_e32 v250, 0x38d1b717, v250
	v_max_f32_e32 v251, 0x38d1b717, v251
	v_pk_mul_f32 v[32:33], v[32:33], v[244:245]
	v_pk_mul_f32 v[34:35], v[34:35], v[246:247]
	v_pk_mul_f32 v[28:29], v[28:29], v[248:249]
	v_pk_mul_f32 v[30:31], v[30:31], v[250:251]
	v_lshlrev_b32_e32 v244, 16, v136
	v_and_b32_e32 v245, 0xffff0000, v136
	v_lshlrev_b32_e32 v246, 16, v137
	v_and_b32_e32 v247, 0xffff0000, v137
	v_lshlrev_b32_e32 v248, 16, v138
	v_and_b32_e32 v249, 0xffff0000, v138
	v_lshlrev_b32_e32 v250, 16, v139
	v_and_b32_e32 v251, 0xffff0000, v139
	v_max_f32_e32 v244, 0x38d1b717, v244
	v_max_f32_e32 v245, 0x38d1b717, v245
	v_max_f32_e32 v246, 0x38d1b717, v246
	v_max_f32_e32 v247, 0x38d1b717, v247
	v_max_f32_e32 v248, 0x38d1b717, v248
	v_max_f32_e32 v249, 0x38d1b717, v249
	v_max_f32_e32 v250, 0x38d1b717, v250
	v_max_f32_e32 v251, 0x38d1b717, v251
	v_rcp_f32_e32 v244, v244
	v_rcp_f32_e32 v245, v245
	v_rcp_f32_e32 v246, v246
	v_rcp_f32_e32 v247, v247
	v_rcp_f32_e32 v248, v248
	v_rcp_f32_e32 v249, v249
	v_rcp_f32_e32 v250, v250
	v_rcp_f32_e32 v251, v251
	s_nop 0
	v_pk_mul_f32 v[32:33], v[32:33], v[244:245]
	v_pk_mul_f32 v[34:35], v[34:35], v[246:247]
	v_pk_mul_f32 v[28:29], v[28:29], v[248:249]
	v_pk_mul_f32 v[30:31], v[30:31], v[250:251]
	v_lshlrev_b32_e32 v244, 16, v140
	v_and_b32_e32 v245, 0xffff0000, v140
	v_lshlrev_b32_e32 v246, 16, v141
	v_and_b32_e32 v247, 0xffff0000, v141
	v_lshlrev_b32_e32 v248, 16, v142
	v_and_b32_e32 v249, 0xffff0000, v142
	v_lshlrev_b32_e32 v250, 16, v143
	v_and_b32_e32 v251, 0xffff0000, v143
	v_max_f32_e32 v244, 0x38d1b717, v244
	v_max_f32_e32 v245, 0x38d1b717, v245
	v_max_f32_e32 v246, 0x38d1b717, v246
	v_max_f32_e32 v247, 0x38d1b717, v247
	v_max_f32_e32 v248, 0x38d1b717, v248
	v_max_f32_e32 v249, 0x38d1b717, v249
	v_max_f32_e32 v250, 0x38d1b717, v250
	v_max_f32_e32 v251, 0x38d1b717, v251
	v_pk_mul_f32 v[24:25], v[24:25], v[244:245]
	v_pk_mul_f32 v[26:27], v[26:27], v[246:247]
	v_pk_mul_f32 v[20:21], v[20:21], v[248:249]
	v_pk_mul_f32 v[22:23], v[22:23], v[250:251]
	v_lshlrev_b32_e32 v244, 16, v144
	v_and_b32_e32 v245, 0xffff0000, v144
	v_lshlrev_b32_e32 v246, 16, v145
	v_and_b32_e32 v247, 0xffff0000, v145
	v_lshlrev_b32_e32 v248, 16, v146
	v_and_b32_e32 v249, 0xffff0000, v146
	v_lshlrev_b32_e32 v250, 16, v147
	v_and_b32_e32 v251, 0xffff0000, v147
	v_max_f32_e32 v244, 0x38d1b717, v244
	v_max_f32_e32 v245, 0x38d1b717, v245
	v_max_f32_e32 v246, 0x38d1b717, v246
	v_max_f32_e32 v247, 0x38d1b717, v247
	v_max_f32_e32 v248, 0x38d1b717, v248
	v_max_f32_e32 v249, 0x38d1b717, v249
	v_max_f32_e32 v250, 0x38d1b717, v250
	v_max_f32_e32 v251, 0x38d1b717, v251
	v_rcp_f32_e32 v244, v244
	v_rcp_f32_e32 v245, v245
	v_rcp_f32_e32 v246, v246
	v_rcp_f32_e32 v247, v247
	v_rcp_f32_e32 v248, v248
	v_rcp_f32_e32 v249, v249
	v_rcp_f32_e32 v250, v250
	v_rcp_f32_e32 v251, v251
	s_nop 0
	v_pk_mul_f32 v[24:25], v[24:25], v[244:245]
	v_pk_mul_f32 v[26:27], v[26:27], v[246:247]
	v_pk_mul_f32 v[20:21], v[20:21], v[248:249]
	v_pk_mul_f32 v[22:23], v[22:23], v[250:251]
	v_lshlrev_b32_e32 v244, 16, v148
	v_and_b32_e32 v245, 0xffff0000, v148
	v_lshlrev_b32_e32 v246, 16, v149
	v_and_b32_e32 v247, 0xffff0000, v149
	v_lshlrev_b32_e32 v248, 16, v150
	v_and_b32_e32 v249, 0xffff0000, v150
	v_lshlrev_b32_e32 v250, 16, v151
	v_and_b32_e32 v251, 0xffff0000, v151
	v_max_f32_e32 v244, 0x38d1b717, v244
	v_max_f32_e32 v245, 0x38d1b717, v245
	v_max_f32_e32 v246, 0x38d1b717, v246
	v_max_f32_e32 v247, 0x38d1b717, v247
	v_max_f32_e32 v248, 0x38d1b717, v248
	v_max_f32_e32 v249, 0x38d1b717, v249
	v_max_f32_e32 v250, 0x38d1b717, v250
	v_max_f32_e32 v251, 0x38d1b717, v251
	v_pk_mul_f32 v[16:17], v[16:17], v[244:245]
	v_pk_mul_f32 v[18:19], v[18:19], v[246:247]
;     __device__ __forceinline__ bool apply(f32x4 (&acc)[2][2][4][2], const pg8::Unit& u, int wr, int wc, int fr, int fq) const {
;     ...
;         const int row0 = u.pm * 256 + wr * 64 + fr, colb = u.pn * 256 + wc * 32 + 8 * fq, br = u.br;
;         const bf16_t* G = (const bf16_t*)(ws + WS_GATE); bf16_t* Mb = (bf16_t*)(ws + WS_HB);
; #pragma unroll
;         for (int ai = 0; ai < 2; ++ai)
; #pragma unroll
;             for (int m = 0; m < 4; ++m)
; #pragma unroll
;                 for (int bj = 0; bj < 2; ++bj) { const int row = row0 + ai * 128 + m * 16, col0 = colb + bj * 128;
;                     float gc[8], gn[8]; load8(G + (size_t)row * GT_COLS + br * 1024 + col0, gc);
;                     if (br < 2) load8(G + (size_t)row * GT_COLS + (br + 1) * 1024 + col0, gn);
;                     else {
; #pragma unroll
;                         for (int j = 0; j < 8; ++j) gn[j] = 1.f; }
;                     float v[8]; const f32x4 v0 = acc[ai][bj][m][0], v1 = acc[ai][bj][m][1];
;                     v[0] = v0.x; v[1] = v0.y; v[2] = v0.z; v[3] = v0.w; v[4] = v1.x; v[5] = v1.y; v[6] = v1.z; v[7] = v1.w;
; #pragma unroll
;                     for (int j = 0; j < 8; ++j) v[j] *= fmaxf(gc[j], 1e-4f);
;                     if (br == 2) store8(Mb + (size_t)row * 1024 + col0, v);
;                     else {
; #pragma unroll
;                         for (int j = 0; j < 8; ++j) v[j] *= __builtin_amdgcn_rcpf(fmaxf(gn[j], 1e-4f));
;                         acc[ai][bj][m][0] = (f32x4){v[0], v[1], v[2], v[3]}; acc[ai][bj][m][1] = (f32x4){v[4], v[5], v[6], v[7]}; }
;                 }
;         return br < 2;
	v_pk_mul_f32 v[12:13], v[12:13], v[248:249]
	v_pk_mul_f32 v[14:15], v[14:15], v[250:251]
	v_lshlrev_b32_e32 v244, 16, v152
	v_and_b32_e32 v245, 0xffff0000, v152
	v_lshlrev_b32_e32 v246, 16, v153
	v_and_b32_e32 v247, 0xffff0000, v153
	v_lshlrev_b32_e32 v248, 16, v154
	v_and_b32_e32 v249, 0xffff0000, v154
	v_lshlrev_b32_e32 v250, 16, v155
	v_and_b32_e32 v251, 0xffff0000, v155
	v_max_f32_e32 v244, 0x38d1b717, v244
	v_max_f32_e32 v245, 0x38d1b717, v245
	v_max_f32_e32 v246, 0x38d1b717, v246
	v_max_f32_e32 v247, 0x38d1b717, v247
	v_max_f32_e32 v248, 0x38d1b717, v248
	v_max_f32_e32 v249, 0x38d1b717, v249
	v_max_f32_e32 v250, 0x38d1b717, v250
	v_max_f32_e32 v251, 0x38d1b717, v251
	v_rcp_f32_e32 v244, v244
	v_rcp_f32_e32 v245, v245
	v_rcp_f32_e32 v246, v246
	v_rcp_f32_e32 v247, v247
	v_rcp_f32_e32 v248, v248
	v_rcp_f32_e32 v249, v249
	v_rcp_f32_e32 v250, v250
	v_rcp_f32_e32 v251, v251
	s_nop 0
	v_pk_mul_f32 v[16:17], v[16:17], v[244:245]
	v_pk_mul_f32 v[18:19], v[18:19], v[246:247]
	v_pk_mul_f32 v[12:13], v[12:13], v[248:249]
	v_pk_mul_f32 v[14:15], v[14:15], v[250:251]
	v_lshlrev_b32_e32 v244, 16, v156
	v_and_b32_e32 v245, 0xffff0000, v156
	v_lshlrev_b32_e32 v246, 16, v157
	v_and_b32_e32 v247, 0xffff0000, v157
	v_lshlrev_b32_e32 v248, 16, v158
	v_and_b32_e32 v249, 0xffff0000, v158
	v_lshlrev_b32_e32 v250, 16, v159
	v_and_b32_e32 v251, 0xffff0000, v159
	v_max_f32_e32 v244, 0x38d1b717, v244
	v_max_f32_e32 v245, 0x38d1b717, v245
	v_max_f32_e32 v246, 0x38d1b717, v246
	v_max_f32_e32 v247, 0x38d1b717, v247
	v_max_f32_e32 v248, 0x38d1b717, v248
	v_max_f32_e32 v249, 0x38d1b717, v249
	v_max_f32_e32 v250, 0x38d1b717, v250
	v_max_f32_e32 v251, 0x38d1b717, v251
	v_pk_mul_f32 v[8:9], v[8:9], v[244:245]
	v_pk_mul_f32 v[10:11], v[10:11], v[246:247]
	v_pk_mul_f32 v[4:5], v[4:5], v[248:249]
	v_pk_mul_f32 v[6:7], v[6:7], v[250:251]
	v_lshlrev_b32_e32 v244, 16, v160
	v_and_b32_e32 v245, 0xffff0000, v160
	v_lshlrev_b32_e32 v246, 16, v161
	v_and_b32_e32 v247, 0xffff0000, v161
	v_lshlrev_b32_e32 v248, 16, v162
	v_and_b32_e32 v249, 0xffff0000, v162
	v_lshlrev_b32_e32 v250, 16, v163
	v_and_b32_e32 v251, 0xffff0000, v163
	v_max_f32_e32 v244, 0x38d1b717, v244
	v_max_f32_e32 v245, 0x38d1b717, v245
	v_max_f32_e32 v246, 0x38d1b717, v246
	v_max_f32_e32 v247, 0x38d1b717, v247
	v_max_f32_e32 v248, 0x38d1b717, v248
	v_max_f32_e32 v249, 0x38d1b717, v249
	v_max_f32_e32 v250, 0x38d1b717, v250
	v_max_f32_e32 v251, 0x38d1b717, v251
	v_rcp_f32_e32 v244, v244
	v_rcp_f32_e32 v245, v245
	v_rcp_f32_e32 v246, v246
	v_rcp_f32_e32 v247, v247
	v_rcp_f32_e32 v248, v248
	v_rcp_f32_e32 v249, v249
	v_rcp_f32_e32 v250, v250
	v_rcp_f32_e32 v251, v251
	s_nop 0
	v_pk_mul_f32 v[8:9], v[8:9], v[244:245]
	v_pk_mul_f32 v[10:11], v[10:11], v[246:247]
	v_pk_mul_f32 v[4:5], v[4:5], v[248:249]
	v_pk_mul_f32 v[6:7], v[6:7], v[250:251]
	s_mov_b64 s[16:17], -1
	s_branch .LBB0_1474
.Lbr_last:
	v_lshl_add_u32 v252, v202, 10, v203
	v_lshlrev_b32_e32 v252, 1, v252
	global_load_dwordx4 v[210:213], v182, s[4:5]
	global_load_dwordx4 v[218:221], v182, s[4:5] offset:256
	global_load_dwordx4 v[226:229], v183, s[4:5]
	global_load_dwordx4 v[234:237], v183, s[4:5] offset:256
	global_load_dwordx4 v[132:135], v184, s[4:5]
	global_load_dwordx4 v[140:143], v184, s[4:5] offset:256
	global_load_dwordx4 v[148:151], v185, s[4:5]
	global_load_dwordx4 v[156:159], v185, s[4:5] offset:256
	s_waitcnt vmcnt(4)
	v_lshlrev_b32_e32 v244, 16, v210
	v_and_b32_e32 v245, 0xffff0000, v210
	v_lshlrev_b32_e32 v246, 16, v211
	v_and_b32_e32 v247, 0xffff0000, v211
	v_lshlrev_b32_e32 v248, 16, v212
	v_and_b32_e32 v249, 0xffff0000, v212
	v_lshlrev_b32_e32 v250, 16, v213
	v_and_b32_e32 v251, 0xffff0000, v213
	v_max_f32_e32 v244, 0x38d1b717, v244
	v_max_f32_e32 v245, 0x38d1b717, v245
	v_max_f32_e32 v246, 0x38d1b717, v246
	v_max_f32_e32 v247, 0x38d1b717, v247
	v_max_f32_e32 v248, 0x38d1b717, v248
	v_max_f32_e32 v249, 0x38d1b717, v249
	v_max_f32_e32 v250, 0x38d1b717, v250
	v_max_f32_e32 v251, 0x38d1b717, v251
	v_pk_mul_f32 v[128:129], v[128:129], v[244:245]
	v_pk_mul_f32 v[130:131], v[130:131], v[246:247]
	v_pk_mul_f32 v[124:125], v[124:125], v[248:249]
	v_pk_mul_f32 v[126:127], v[126:127], v[250:251]
	v_cvt_pk_bf16_f32 v244, v128, v129
	v_cvt_pk_bf16_f32 v245, v130, v131
	v_cvt_pk_bf16_f32 v246, v124, v125
	v_cvt_pk_bf16_f32 v247, v126, v127
	global_store_dwordx4 v252, v[244:247], s[6:7]
	s_nop 1
	v_lshlrev_b32_e32 v244, 16, v218
	v_and_b32_e32 v245, 0xffff0000, v218
	v_lshlrev_b32_e32 v246, 16, v219
	v_and_b32_e32 v247, 0xffff0000, v219
	v_lshlrev_b32_e32 v248, 16, v220
	v_and_b32_e32 v249, 0xffff0000, v220
	v_lshlrev_b32_e32 v250, 16, v221
	v_and_b32_e32 v251, 0xffff0000, v221
	v_max_f32_e32 v244, 0x38d1b717, v244
	v_max_f32_e32 v245, 0x38d1b717, v245
	v_max_f32_e32 v246, 0x38d1b717, v246
	v_max_f32_e32 v247, 0x38d1b717, v247
	v_max_f32_e32 v248, 0x38d1b717, v248
	v_max_f32_e32 v249, 0x38d1b717, v249
	v_max_f32_e32 v250, 0x38d1b717, v250
	v_max_f32_e32 v251, 0x38d1b717, v251
	v_pk_mul_f32 v[120:121], v[120:121], v[244:245]
	v_pk_mul_f32 v[122:123], v[122:123], v[246:247]
	v_pk_mul_f32 v[116:117], v[116:117], v[248:249]
	v_pk_mul_f32 v[118:119], v[118:119], v[250:251]
	v_cvt_pk_bf16_f32 v244, v120, v121
	v_cvt_pk_bf16_f32 v245, v122, v123
	v_cvt_pk_bf16_f32 v246, v116, v117
	v_cvt_pk_bf16_f32 v247, v118, v119
	v_add_u32_e32 v243, 0x100, v252
	global_store_dwordx4 v243, v[244:247], s[6:7]
	s_nop 1
	v_lshlrev_b32_e32 v244, 16, v226
	v_and_b32_e32 v245, 0xffff0000, v226
	v_lshlrev_b32_e32 v246, 16, v227
	v_and_b32_e32 v247, 0xffff0000, v227
	v_lshlrev_b32_e32 v248, 16, v228
	v_and_b32_e32 v249, 0xffff0000, v228
	v_lshlrev_b32_e32 v250, 16, v229
;     __device__ __forceinline__ bool apply(f32x4 (&acc)[2][2][4][2], const pg8::Unit& u, int wr, int wc, int fr, int fq) const {
;     ...
;                 for (int bj = 0; bj < 2; ++bj) { const int row = row0 + ai * 128 + m * 16, col0 = colb + bj * 128;
;                     float gc[8], gn[8]; load8(G + (size_t)row * GT_COLS + br * 1024 + col0, gc);
;                     if (br < 2) load8(G + (size_t)row * GT_COLS + (br + 1) * 1024 + col0, gn);
;                     else {
; #pragma unroll
;                         for (int j = 0; j < 8; ++j) gn[j] = 1.f; }
;                     float v[8]; const f32x4 v0 = acc[ai][bj][m][0], v1 = acc[ai][bj][m][1];
;                     v[0] = v0.x; v[1] = v0.y; v[2] = v0.z; v[3] = v0.w; v[4] = v1.x; v[5] = v1.y; v[6] = v1.z; v[7] = v1.w;
; #pragma unroll
;                     for (int j = 0; j < 8; ++j) v[j] *= fmaxf(gc[j], 1e-4f);
;                     if (br == 2) store8(Mb + (size_t)row * 1024 + col0, v);
	v_and_b32_e32 v251, 0xffff0000, v229
	v_max_f32_e32 v244, 0x38d1b717, v244
	v_max_f32_e32 v245, 0x38d1b717, v245
	v_max_f32_e32 v246, 0x38d1b717, v246
	v_max_f32_e32 v247, 0x38d1b717, v247
	v_max_f32_e32 v248, 0x38d1b717, v248
	v_max_f32_e32 v249, 0x38d1b717, v249
	v_max_f32_e32 v250, 0x38d1b717, v250
	v_max_f32_e32 v251, 0x38d1b717, v251
	v_pk_mul_f32 v[112:113], v[112:113], v[244:245]
	v_pk_mul_f32 v[114:115], v[114:115], v[246:247]
	v_pk_mul_f32 v[108:109], v[108:109], v[248:249]
	v_pk_mul_f32 v[110:111], v[110:111], v[250:251]
	v_cvt_pk_bf16_f32 v244, v112, v113
	v_cvt_pk_bf16_f32 v245, v114, v115
	v_cvt_pk_bf16_f32 v246, v108, v109
	v_cvt_pk_bf16_f32 v247, v110, v111
	v_add_u32_e32 v243, 0x8000, v252
	global_store_dwordx4 v243, v[244:247], s[6:7]
	s_nop 1
	v_lshlrev_b32_e32 v244, 16, v234
	v_and_b32_e32 v245, 0xffff0000, v234
	v_lshlrev_b32_e32 v246, 16, v235
	v_and_b32_e32 v247, 0xffff0000, v235
	v_lshlrev_b32_e32 v248, 16, v236
	v_and_b32_e32 v249, 0xffff0000, v236
	v_lshlrev_b32_e32 v250, 16, v237
	v_and_b32_e32 v251, 0xffff0000, v237
	v_max_f32_e32 v244, 0x38d1b717, v244
	v_max_f32_e32 v245, 0x38d1b717, v245
	v_max_f32_e32 v246, 0x38d1b717, v246
	v_max_f32_e32 v247, 0x38d1b717, v247
	v_max_f32_e32 v248, 0x38d1b717, v248
	v_max_f32_e32 v249, 0x38d1b717, v249
	v_max_f32_e32 v250, 0x38d1b717, v250
	v_max_f32_e32 v251, 0x38d1b717, v251
	v_pk_mul_f32 v[104:105], v[104:105], v[244:245]
	v_pk_mul_f32 v[106:107], v[106:107], v[246:247]
	v_pk_mul_f32 v[100:101], v[100:101], v[248:249]
	v_pk_mul_f32 v[102:103], v[102:103], v[250:251]
	v_cvt_pk_bf16_f32 v244, v104, v105
	v_cvt_pk_bf16_f32 v245, v106, v107
	v_cvt_pk_bf16_f32 v246, v100, v101
	v_cvt_pk_bf16_f32 v247, v102, v103
	v_add_u32_e32 v243, 0x8100, v252
	global_store_dwordx4 v243, v[244:247], s[6:7]
	s_nop 1
	global_load_dwordx4 v[210:213], v190, s[4:5]
	global_load_dwordx4 v[218:221], v190, s[4:5] offset:256
	global_load_dwordx4 v[226:229], v191, s[4:5]
	global_load_dwordx4 v[234:237], v191, s[4:5] offset:256
	s_waitcnt vmcnt(4)
	v_lshlrev_b32_e32 v244, 16, v132
	v_and_b32_e32 v245, 0xffff0000, v132
	v_lshlrev_b32_e32 v246, 16, v133
	v_and_b32_e32 v247, 0xffff0000, v133
	v_lshlrev_b32_e32 v248, 16, v134
	v_and_b32_e32 v249, 0xffff0000, v134
	v_lshlrev_b32_e32 v250, 16, v135
	v_and_b32_e32 v251, 0xffff0000, v135
	v_max_f32_e32 v244, 0x38d1b717, v244
	v_max_f32_e32 v245, 0x38d1b717, v245
	v_max_f32_e32 v246, 0x38d1b717, v246
	v_max_f32_e32 v247, 0x38d1b717, v247
	v_max_f32_e32 v248, 0x38d1b717, v248
	v_max_f32_e32 v249, 0x38d1b717, v249
	v_max_f32_e32 v250, 0x38d1b717, v250
	v_max_f32_e32 v251, 0x38d1b717, v251
	v_pk_mul_f32 v[96:97], v[96:97], v[244:245]
	v_pk_mul_f32 v[98:99], v[98:99], v[246:247]
	v_pk_mul_f32 v[92:93], v[92:93], v[248:249]
	v_pk_mul_f32 v[94:95], v[94:95], v[250:251]
	v_cvt_pk_bf16_f32 v244, v96, v97
	v_cvt_pk_bf16_f32 v245, v98, v99
	v_cvt_pk_bf16_f32 v246, v92, v93
	v_cvt_pk_bf16_f32 v247, v94, v95
	v_add_u32_e32 v243, 0x10000, v252
	global_store_dwordx4 v243, v[244:247], s[6:7]
	s_nop 1
	v_lshlrev_b32_e32 v244, 16, v140
	v_and_b32_e32 v245, 0xffff0000, v140
	v_lshlrev_b32_e32 v246, 16, v141
	v_and_b32_e32 v247, 0xffff0000, v141
	v_lshlrev_b32_e32 v248, 16, v142
	v_and_b32_e32 v249, 0xffff0000, v142
	v_lshlrev_b32_e32 v250, 16, v143
	v_and_b32_e32 v251, 0xffff0000, v143
	v_max_f32_e32 v244, 0x38d1b717, v244
	v_max_f32_e32 v245, 0x38d1b717, v245
	v_max_f32_e32 v246, 0x38d1b717, v246
	v_max_f32_e32 v247, 0x38d1b717, v247
	v_max_f32_e32 v248, 0x38d1b717, v248
	v_max_f32_e32 v249, 0x38d1b717, v249
	v_max_f32_e32 v250, 0x38d1b717, v250
	v_max_f32_e32 v251, 0x38d1b717, v251
	v_pk_mul_f32 v[88:89], v[88:89], v[244:245]
	v_pk_mul_f32 v[90:91], v[90:91], v[246:247]
	v_pk_mul_f32 v[84:85], v[84:85], v[248:249]
	v_pk_mul_f32 v[86:87], v[86:87], v[250:251]
	v_cvt_pk_bf16_f32 v244, v88, v89
	v_cvt_pk_bf16_f32 v245, v90, v91
	v_cvt_pk_bf16_f32 v246, v84, v85
	v_cvt_pk_bf16_f32 v247, v86, v87
	v_add_u32_e32 v243, 0x10100, v252
	global_store_dwordx4 v243, v[244:247], s[6:7]
	s_nop 1
	v_lshlrev_b32_e32 v244, 16, v148
	v_and_b32_e32 v245, 0xffff0000, v148
	v_lshlrev_b32_e32 v246, 16, v149
	v_and_b32_e32 v247, 0xffff0000, v149
	v_lshlrev_b32_e32 v248, 16, v150
	v_and_b32_e32 v249, 0xffff0000, v150
	v_lshlrev_b32_e32 v250, 16, v151
	v_and_b32_e32 v251, 0xffff0000, v151
	v_max_f32_e32 v244, 0x38d1b717, v244
	v_max_f32_e32 v245, 0x38d1b717, v245
	v_max_f32_e32 v246, 0x38d1b717, v246
	v_max_f32_e32 v247, 0x38d1b717, v247
	v_max_f32_e32 v248, 0x38d1b717, v248
	v_max_f32_e32 v249, 0x38d1b717, v249
	v_max_f32_e32 v250, 0x38d1b717, v250
	v_max_f32_e32 v251, 0x38d1b717, v251
	v_pk_mul_f32 v[80:81], v[80:81], v[244:245]
	v_pk_mul_f32 v[82:83], v[82:83], v[246:247]
	v_pk_mul_f32 v[76:77], v[76:77], v[248:249]
	v_pk_mul_f32 v[78:79], v[78:79], v[250:251]
	v_cvt_pk_bf16_f32 v244, v80, v81
	v_cvt_pk_bf16_f32 v245, v82, v83
	v_cvt_pk_bf16_f32 v246, v76, v77
	v_cvt_pk_bf16_f32 v247, v78, v79
	v_add_u32_e32 v243, 0x18000, v252
	global_store_dwordx4 v243, v[244:247], s[6:7]
	s_nop 1
	v_lshlrev_b32_e32 v244, 16, v156
	v_and_b32_e32 v245, 0xffff0000, v156
	v_lshlrev_b32_e32 v246, 16, v157
	v_and_b32_e32 v247, 0xffff0000, v157
	v_lshlrev_b32_e32 v248, 16, v158
	v_and_b32_e32 v249, 0xffff0000, v158
	v_lshlrev_b32_e32 v250, 16, v159
	v_and_b32_e32 v251, 0xffff0000, v159
	v_max_f32_e32 v244, 0x38d1b717, v244
	v_max_f32_e32 v245, 0x38d1b717, v245
	v_max_f32_e32 v246, 0x38d1b717, v246
	v_max_f32_e32 v247, 0x38d1b717, v247
	v_max_f32_e32 v248, 0x38d1b717, v248
	v_max_f32_e32 v249, 0x38d1b717, v249
	v_max_f32_e32 v250, 0x38d1b717, v250
	v_max_f32_e32 v251, 0x38d1b717, v251
	v_pk_mul_f32 v[72:73], v[72:73], v[244:245]
	v_pk_mul_f32 v[74:75], v[74:75], v[246:247]
	v_pk_mul_f32 v[68:69], v[68:69], v[248:249]
	v_pk_mul_f32 v[70:71], v[70:71], v[250:251]
	v_cvt_pk_bf16_f32 v244, v72, v73
	v_cvt_pk_bf16_f32 v245, v74, v75
	v_cvt_pk_bf16_f32 v246, v68, v69
	v_cvt_pk_bf16_f32 v247, v70, v71
	v_add_u32_e32 v243, 0x18100, v252
	global_store_dwordx4 v243, v[244:247], s[6:7]
	s_nop 1
	global_load_dwordx4 v[132:135], v200, s[4:5]
	global_load_dwordx4 v[140:143], v200, s[4:5] offset:256
	global_load_dwordx4 v[148:151], v201, s[4:5]
	global_load_dwordx4 v[156:159], v201, s[4:5] offset:256
	s_waitcnt vmcnt(4)
;     __device__ __forceinline__ bool apply(f32x4 (&acc)[2][2][4][2], const pg8::Unit& u, int wr, int wc, int fr, int fq) const {
;     ...
;                 for (int bj = 0; bj < 2; ++bj) { const int row = row0 + ai * 128 + m * 16, col0 = colb + bj * 128;
;                     float gc[8], gn[8]; load8(G + (size_t)row * GT_COLS + br * 1024 + col0, gc);
;                     if (br < 2) load8(G + (size_t)row * GT_COLS + (br + 1) * 1024 + col0, gn);
;                     else {
; #pragma unroll
;                         for (int j = 0; j < 8; ++j) gn[j] = 1.f; }
;                     float v[8]; const f32x4 v0 = acc[ai][bj][m][0], v1 = acc[ai][bj][m][1];
;                     v[0] = v0.x; v[1] = v0.y; v[2] = v0.z; v[3] = v0.w; v[4] = v1.x; v[5] = v1.y; v[6] = v1.z; v[7] = v1.w;
; #pragma unroll
;                     for (int j = 0; j < 8; ++j) v[j] *= fmaxf(gc[j], 1e-4f);
;                     if (br == 2) store8(Mb + (size_t)row * 1024 + col0, v);
	v_lshlrev_b32_e32 v244, 16, v210
	v_and_b32_e32 v245, 0xffff0000, v210
	v_lshlrev_b32_e32 v246, 16, v211
	v_and_b32_e32 v247, 0xffff0000, v211
	v_lshlrev_b32_e32 v248, 16, v212
	v_and_b32_e32 v249, 0xffff0000, v212
	v_lshlrev_b32_e32 v250, 16, v213
	v_and_b32_e32 v251, 0xffff0000, v213
	v_max_f32_e32 v244, 0x38d1b717, v244
	v_max_f32_e32 v245, 0x38d1b717, v245
	v_max_f32_e32 v246, 0x38d1b717, v246
	v_max_f32_e32 v247, 0x38d1b717, v247
	v_max_f32_e32 v248, 0x38d1b717, v248
	v_max_f32_e32 v249, 0x38d1b717, v249
	v_max_f32_e32 v250, 0x38d1b717, v250
	v_max_f32_e32 v251, 0x38d1b717, v251
	v_pk_mul_f32 v[64:65], v[64:65], v[244:245]
	v_pk_mul_f32 v[66:67], v[66:67], v[246:247]
	v_pk_mul_f32 v[60:61], v[60:61], v[248:249]
	v_pk_mul_f32 v[62:63], v[62:63], v[250:251]
	v_cvt_pk_bf16_f32 v244, v64, v65
	v_cvt_pk_bf16_f32 v245, v66, v67
	v_cvt_pk_bf16_f32 v246, v60, v61
	v_cvt_pk_bf16_f32 v247, v62, v63
	v_add_u32_e32 v243, 0x40000, v252
	global_store_dwordx4 v243, v[244:247], s[6:7]
	s_nop 1
	v_lshlrev_b32_e32 v244, 16, v218
	v_and_b32_e32 v245, 0xffff0000, v218
	v_lshlrev_b32_e32 v246, 16, v219
	v_and_b32_e32 v247, 0xffff0000, v219
	v_lshlrev_b32_e32 v248, 16, v220
	v_and_b32_e32 v249, 0xffff0000, v220
	v_lshlrev_b32_e32 v250, 16, v221
	v_and_b32_e32 v251, 0xffff0000, v221
	v_max_f32_e32 v244, 0x38d1b717, v244
	v_max_f32_e32 v245, 0x38d1b717, v245
	v_max_f32_e32 v246, 0x38d1b717, v246
	v_max_f32_e32 v247, 0x38d1b717, v247
	v_max_f32_e32 v248, 0x38d1b717, v248
	v_max_f32_e32 v249, 0x38d1b717, v249
	v_max_f32_e32 v250, 0x38d1b717, v250
	v_max_f32_e32 v251, 0x38d1b717, v251
	v_pk_mul_f32 v[56:57], v[56:57], v[244:245]
	v_pk_mul_f32 v[58:59], v[58:59], v[246:247]
	v_pk_mul_f32 v[52:53], v[52:53], v[248:249]
	v_pk_mul_f32 v[54:55], v[54:55], v[250:251]
	v_cvt_pk_bf16_f32 v244, v56, v57
	v_cvt_pk_bf16_f32 v245, v58, v59
	v_cvt_pk_bf16_f32 v246, v52, v53
	v_cvt_pk_bf16_f32 v247, v54, v55
	v_add_u32_e32 v243, 0x40100, v252
	global_store_dwordx4 v243, v[244:247], s[6:7]
	s_nop 1
	v_lshlrev_b32_e32 v244, 16, v226
	v_and_b32_e32 v245, 0xffff0000, v226
	v_lshlrev_b32_e32 v246, 16, v227
	v_and_b32_e32 v247, 0xffff0000, v227
	v_lshlrev_b32_e32 v248, 16, v228
	v_and_b32_e32 v249, 0xffff0000, v228
	v_lshlrev_b32_e32 v250, 16, v229
	v_and_b32_e32 v251, 0xffff0000, v229
	v_max_f32_e32 v244, 0x38d1b717, v244
	v_max_f32_e32 v245, 0x38d1b717, v245
	v_max_f32_e32 v246, 0x38d1b717, v246
	v_max_f32_e32 v247, 0x38d1b717, v247
	v_max_f32_e32 v248, 0x38d1b717, v248
	v_max_f32_e32 v249, 0x38d1b717, v249
	v_max_f32_e32 v250, 0x38d1b717, v250
	v_max_f32_e32 v251, 0x38d1b717, v251
	v_pk_mul_f32 v[48:49], v[48:49], v[244:245]
	v_pk_mul_f32 v[50:51], v[50:51], v[246:247]
	v_pk_mul_f32 v[44:45], v[44:45], v[248:249]
	v_pk_mul_f32 v[46:47], v[46:47], v[250:251]
	v_cvt_pk_bf16_f32 v244, v48, v49
	v_cvt_pk_bf16_f32 v245, v50, v51
	v_cvt_pk_bf16_f32 v246, v44, v45
	v_cvt_pk_bf16_f32 v247, v46, v47
	v_add_u32_e32 v243, 0x48000, v252
	global_store_dwordx4 v243, v[244:247], s[6:7]
	s_nop 1
	v_lshlrev_b32_e32 v244, 16, v234
	v_and_b32_e32 v245, 0xffff0000, v234
	v_lshlrev_b32_e32 v246, 16, v235
	v_and_b32_e32 v247, 0xffff0000, v235
	v_lshlrev_b32_e32 v248, 16, v236
	v_and_b32_e32 v249, 0xffff0000, v236
	v_lshlrev_b32_e32 v250, 16, v237
	v_and_b32_e32 v251, 0xffff0000, v237
	v_max_f32_e32 v244, 0x38d1b717, v244
	v_max_f32_e32 v245, 0x38d1b717, v245
	v_max_f32_e32 v246, 0x38d1b717, v246
	v_max_f32_e32 v247, 0x38d1b717, v247
	v_max_f32_e32 v248, 0x38d1b717, v248
	v_max_f32_e32 v249, 0x38d1b717, v249
	v_max_f32_e32 v250, 0x38d1b717, v250
	v_max_f32_e32 v251, 0x38d1b717, v251
	v_pk_mul_f32 v[40:41], v[40:41], v[244:245]
	v_pk_mul_f32 v[42:43], v[42:43], v[246:247]
	v_pk_mul_f32 v[36:37], v[36:37], v[248:249]
	v_pk_mul_f32 v[38:39], v[38:39], v[250:251]
	v_cvt_pk_bf16_f32 v244, v40, v41
	v_cvt_pk_bf16_f32 v245, v42, v43
	v_cvt_pk_bf16_f32 v246, v36, v37
	v_cvt_pk_bf16_f32 v247, v38, v39
	v_add_u32_e32 v243, 0x48100, v252
	global_store_dwordx4 v243, v[244:247], s[6:7]
	s_nop 1
	s_waitcnt vmcnt(0)
;     __device__ __forceinline__ bool apply(f32x4 (&acc)[2][2][4][2], const pg8::Unit& u, int wr, int wc, int fr, int fq) const {
;     ...
;                 for (int bj = 0; bj < 2; ++bj) { const int row = row0 + ai * 128 + m * 16, col0 = colb + bj * 128;
;                     float gc[8], gn[8]; load8(G + (size_t)row * GT_COLS + br * 1024 + col0, gc);
;                     if (br < 2) load8(G + (size_t)row * GT_COLS + (br + 1) * 1024 + col0, gn);
;                     else {
; #pragma unroll
;                         for (int j = 0; j < 8; ++j) gn[j] = 1.f; }
;                     float v[8]; const f32x4 v0 = acc[ai][bj][m][0], v1 = acc[ai][bj][m][1];
;                     v[0] = v0.x; v[1] = v0.y; v[2] = v0.z; v[3] = v0.w; v[4] = v1.x; v[5] = v1.y; v[6] = v1.z; v[7] = v1.w;
; #pragma unroll
;                     for (int j = 0; j < 8; ++j) v[j] *= fmaxf(gc[j], 1e-4f);
;                     if (br == 2) store8(Mb + (size_t)row * 1024 + col0, v);
	v_lshlrev_b32_e32 v244, 16, v132
	v_and_b32_e32 v245, 0xffff0000, v132
	v_lshlrev_b32_e32 v246, 16, v133
	v_and_b32_e32 v247, 0xffff0000, v133
	v_lshlrev_b32_e32 v248, 16, v134
	v_and_b32_e32 v249, 0xffff0000, v134
	v_lshlrev_b32_e32 v250, 16, v135
	v_and_b32_e32 v251, 0xffff0000, v135
	v_max_f32_e32 v244, 0x38d1b717, v244
	v_max_f32_e32 v245, 0x38d1b717, v245
	v_max_f32_e32 v246, 0x38d1b717, v246
	v_max_f32_e32 v247, 0x38d1b717, v247
	v_max_f32_e32 v248, 0x38d1b717, v248
	v_max_f32_e32 v249, 0x38d1b717, v249
	v_max_f32_e32 v250, 0x38d1b717, v250
	v_max_f32_e32 v251, 0x38d1b717, v251
	v_pk_mul_f32 v[32:33], v[32:33], v[244:245]
	v_pk_mul_f32 v[34:35], v[34:35], v[246:247]
	v_pk_mul_f32 v[28:29], v[28:29], v[248:249]
	v_pk_mul_f32 v[30:31], v[30:31], v[250:251]
	v_cvt_pk_bf16_f32 v244, v32, v33
	v_cvt_pk_bf16_f32 v245, v34, v35
	v_cvt_pk_bf16_f32 v246, v28, v29
	v_cvt_pk_bf16_f32 v247, v30, v31
	v_add_u32_e32 v243, 0x50000, v252
	global_store_dwordx4 v243, v[244:247], s[6:7]
	s_nop 1
	v_lshlrev_b32_e32 v244, 16, v140
	v_and_b32_e32 v245, 0xffff0000, v140
	v_lshlrev_b32_e32 v246, 16, v141
	v_and_b32_e32 v247, 0xffff0000, v141
	v_lshlrev_b32_e32 v248, 16, v142
	v_and_b32_e32 v249, 0xffff0000, v142
	v_lshlrev_b32_e32 v250, 16, v143
	v_and_b32_e32 v251, 0xffff0000, v143
	v_max_f32_e32 v244, 0x38d1b717, v244
	v_max_f32_e32 v245, 0x38d1b717, v245
	v_max_f32_e32 v246, 0x38d1b717, v246
	v_max_f32_e32 v247, 0x38d1b717, v247
	v_max_f32_e32 v248, 0x38d1b717, v248
	v_max_f32_e32 v249, 0x38d1b717, v249
	v_max_f32_e32 v250, 0x38d1b717, v250
	v_max_f32_e32 v251, 0x38d1b717, v251
	v_pk_mul_f32 v[24:25], v[24:25], v[244:245]
	v_pk_mul_f32 v[26:27], v[26:27], v[246:247]
	v_pk_mul_f32 v[20:21], v[20:21], v[248:249]
	v_pk_mul_f32 v[22:23], v[22:23], v[250:251]
	v_cvt_pk_bf16_f32 v244, v24, v25
	v_cvt_pk_bf16_f32 v245, v26, v27
	v_cvt_pk_bf16_f32 v246, v20, v21
	v_cvt_pk_bf16_f32 v247, v22, v23
	v_add_u32_e32 v243, 0x50100, v252
	global_store_dwordx4 v243, v[244:247], s[6:7]
	s_nop 1
	v_lshlrev_b32_e32 v244, 16, v148
	v_and_b32_e32 v245, 0xffff0000, v148
	v_lshlrev_b32_e32 v246, 16, v149
	v_and_b32_e32 v247, 0xffff0000, v149
	v_lshlrev_b32_e32 v248, 16, v150
	v_and_b32_e32 v249, 0xffff0000, v150
	v_lshlrev_b32_e32 v250, 16, v151
	v_and_b32_e32 v251, 0xffff0000, v151
	v_max_f32_e32 v244, 0x38d1b717, v244
	v_max_f32_e32 v245, 0x38d1b717, v245
	v_max_f32_e32 v246, 0x38d1b717, v246
	v_max_f32_e32 v247, 0x38d1b717, v247
	v_max_f32_e32 v248, 0x38d1b717, v248
	v_max_f32_e32 v249, 0x38d1b717, v249
	v_max_f32_e32 v250, 0x38d1b717, v250
	v_max_f32_e32 v251, 0x38d1b717, v251
	v_pk_mul_f32 v[16:17], v[16:17], v[244:245]
	v_pk_mul_f32 v[18:19], v[18:19], v[246:247]
	v_pk_mul_f32 v[12:13], v[12:13], v[248:249]
	v_pk_mul_f32 v[14:15], v[14:15], v[250:251]
	v_cvt_pk_bf16_f32 v244, v16, v17
	v_cvt_pk_bf16_f32 v245, v18, v19
	v_cvt_pk_bf16_f32 v246, v12, v13
	v_cvt_pk_bf16_f32 v247, v14, v15
	v_add_u32_e32 v243, 0x58000, v252
	global_store_dwordx4 v243, v[244:247], s[6:7]
	s_nop 1
	v_lshlrev_b32_e32 v244, 16, v156
	v_and_b32_e32 v245, 0xffff0000, v156
	v_lshlrev_b32_e32 v246, 16, v157
	v_and_b32_e32 v247, 0xffff0000, v157
	v_lshlrev_b32_e32 v248, 16, v158
	v_and_b32_e32 v249, 0xffff0000, v158
	v_lshlrev_b32_e32 v250, 16, v159
	v_and_b32_e32 v251, 0xffff0000, v159
	v_max_f32_e32 v244, 0x38d1b717, v244
	v_max_f32_e32 v245, 0x38d1b717, v245
	v_max_f32_e32 v246, 0x38d1b717, v246
	v_max_f32_e32 v247, 0x38d1b717, v247
	v_max_f32_e32 v248, 0x38d1b717, v248
	v_max_f32_e32 v249, 0x38d1b717, v249
	v_max_f32_e32 v250, 0x38d1b717, v250
	v_max_f32_e32 v251, 0x38d1b717, v251
	v_pk_mul_f32 v[8:9], v[8:9], v[244:245]
	v_pk_mul_f32 v[10:11], v[10:11], v[246:247]
	v_pk_mul_f32 v[4:5], v[4:5], v[248:249]
	v_pk_mul_f32 v[6:7], v[6:7], v[250:251]
	v_cvt_pk_bf16_f32 v244, v8, v9
	v_cvt_pk_bf16_f32 v245, v10, v11
	v_cvt_pk_bf16_f32 v246, v4, v5
	v_cvt_pk_bf16_f32 v247, v6, v7
	v_add_u32_e32 v243, 0x58100, v252
	global_store_dwordx4 v243, v[244:247], s[6:7]
	s_nop 1
	s_mov_b64 s[16:17], 0
	s_branch .LBB0_1474
